# attention loop: K/V tile prefetch uses scalar base + 32-bit lane offset (saddr form), tile pointers advanced by SALU; 19 VALU pointer ops per iteration removed
# baseline (speedup 1.0000x reference)
; #define VMW() asm volatile("s_waitcnt vmcnt(0)" ::: "memory")
; #define SLOAD_H(Kp, Vp, k0) do { S.st_v0 = load8(ROW(Vp, k0, sr)); S.st_v1 = load8(ROW(Vp, k0, 32 + sr));              \
;                          S.st_k0 = load8(ROW(Kp, k0, sr)); S.st_k1 = load8(ROW(Kp, k0, 32 + sr)); } while (0)
; #define SWRITE_HK(bf) do { *(bf16x8*)(K_lds + (bf) * SHM_K + kws) = S.st_k0; *(bf16x8*)(K_lds + (bf) * SHM_K + kws + 32 * 256) = S.st_k1; } while (0)
; __device__ __forceinline__ void attn_prime(const BlockRef& cur, char* lds, Seam& S) {
;     const int tid = threadIdx.x, wid = __builtin_amdgcn_readfirstlane(tid >> 6), lane = tid & 63, r32 = lane & 31, hi = lane >> 5;
;     const int sr = tid >> 4, sc = (tid & 15) * 8, kws = KSWZ(sr, sc * 2); char* K_lds = lds + 2 * SHM_V;
; #pragma unroll
;     for (int d0 = 0; d0 < 8; ++d0) S.qr[d0] = load8(cur.Q + (size_t)(wid * QBLK + r32) * LD + d0 * 16 + hi * 8);
;     SLOAD_H(cur.K, cur.V, 0); VMW(); SWRITE_HK(0);
;     __syncthreads();
; __device__ __forceinline__ void attn_phase(char* lds, const bf16* Q, const bf16* K, const bf16* V, bf16* O, const unsigned long long* MW, int first, int stride) {
;     constexpr int total = (DUP_PHASE == 5) ? 1024 : 512;
;     int L = first; if (L >= total) return;
;     Item it = decode(L); int pass = 0;
;     BlockRef cur = mkref(it, 0, Q, K, V, O, MW);
.LBB0_1289:
	s_cmp_lt_i32 s54, 6
	s_cselect_b64 s[8:9], -1, 0
	s_and_b64 s[0:1], s[8:9], s[0:1]
	s_andn2_b64 vcc, exec, s[0:1]
	s_cbranch_vccnz .LBB0_1447
	s_cmpk_gt_i32 s2, 0x1ff
	s_cbranch_scc1 .LBB0_1447
	s_add_u32 s3, s52, 0xc000000
	s_addc_u32 s15, s53, 0
	s_add_u32 s33, s52, 0x10000000
	s_addc_u32 s35, s53, 0
	s_add_u32 s56, s52, 0x14000000
	s_addc_u32 s57, s53, 0
	s_add_u32 s58, s52, 0x2e00000
	s_addc_u32 s59, s53, 0
	s_lshl_b32 s4, s2, 3
	s_bfe_u32 s1, s2, 0x30003
	s_and_b32 s4, s4, 56
	s_lshl_b32 s5, s4, 9
	s_lshl_b32 s38, s1, 8
	s_bfe_u32 s0, s2, 0x30006
	s_xor_b32 s73, s1, 15
	s_or_b32 s1, s5, s38
	s_or_b32 s72, s4, s0
	s_lshl_b32 s5, s1, 11
	s_add_u32 s6, s3, s5
	s_addc_u32 s7, s15, 0
	s_lshl_b32 s0, s0, 8
	s_add_u32 s10, s6, s0
	s_addc_u32 s11, s7, 0
	s_add_u32 s5, s30, s5
	s_addc_u32 s6, s31, 0
	s_add_u32 s66, s5, s0
	s_addc_u32 s67, s6, 0
	s_lshl_b32 s4, s4, 20
	s_add_u32 s5, s33, s4
	s_addc_u32 s7, s35, 0
	s_add_u32 s6, s5, s0
	s_addc_u32 s7, s7, 0
	s_add_u32 s4, s56, s4
	s_addc_u32 s5, s57, 0
	s_add_u32 s70, s4, s0
	s_addc_u32 s71, s5, 0
	s_lshl_b32 s0, s1, 9
	s_add_u32 s68, s58, s0
	v_readfirstlane_b32 s0, v0
	s_addc_u32 s69, s59, 0
	s_lshr_b32 s0, s0, 1
	s_waitcnt vmcnt(0)
	v_and_b32_e32 v30, 31, v0
	s_and_b32 s0, s0, 0x7fffffe0
	v_or_b32_e32 v166, s0, v30
	v_mov_b32_e32 v167, 0
	v_lshlrev_b64 v[2:3], 11, v[166:167]
	v_lshrrev_b32_e32 v1, 1, v0
	v_lshl_add_u64 v[2:3], s[10:11], 0, v[2:3]
	v_and_b32_e32 v166, 16, v1
	v_lshrrev_b32_e32 v1, 4, v0
	v_lshlrev_b32_e32 v13, 3, v0
	v_lshl_add_u64 v[10:11], v[2:3], 0, v[166:167]
	v_and_b32_e32 v12, 0x78, v13
	v_lshlrev_b32_e32 v166, 11, v1
	v_lshlrev_b32_e32 v14, 1, v12
	v_mov_b32_e32 v15, v167
	v_lshl_add_u64 v[2:3], s[6:7], 0, v[166:167]
	s_mov_b32 s0, 0x10000
	v_lshl_add_u64 v[16:17], v[2:3], 0, v[14:15]
	v_add_co_u32_e32 v18, vcc, s0, v16
	v_bfe_u32 v21, v0, 4, 2
	s_nop 0
	v_addc_co_u32_e32 v19, vcc, 0, v17, vcc
	global_load_dwordx4 v[2:5], v[16:17], off
	global_load_dwordx4 v[6:9], v[18:19], off
	global_load_dwordx4 v[126:129], v[10:11], off
	global_load_dwordx4 v[122:125], v[10:11], off offset:32
	global_load_dwordx4 v[118:121], v[10:11], off offset:64
	global_load_dwordx4 v[114:117], v[10:11], off offset:96
	global_load_dwordx4 v[110:113], v[10:11], off offset:128
	global_load_dwordx4 v[106:109], v[10:11], off offset:160
	global_load_dwordx4 v[102:105], v[10:11], off offset:192
	global_load_dwordx4 v[98:101], v[10:11], off offset:224
	v_lshl_add_u64 v[10:11], s[70:71], 0, v[166:167]
	v_lshrrev_b32_e32 v18, 3, v0
	v_lshl_add_u64 v[10:11], v[10:11], 0, v[14:15]
	v_lshrrev_b32_e32 v19, 5, v0
	v_and_b32_e32 v25, 8, v18
	v_add_co_u32_e32 v18, vcc, s0, v10
	v_and_or_b32 v21, v19, 4, v21
	s_nop 0
	v_addc_co_u32_e32 v19, vcc, 0, v11, vcc
	global_load_dwordx4 v[130:133], v[10:11], off
	global_load_dwordx4 v[134:137], v[18:19], off
	s_movk_i32 s1, 0x70
	v_lshlrev_b32_e32 v24, 8, v1
	v_lshlrev_b32_e32 v16, 10, v1
	v_or_b32_e32 v27, 32, v1
	v_and_or_b32 v1, v1, 16, v25
	v_bitop3_b32 v15, v14, v0, s1 bitop3:0x78
	v_lshrrev_b32_e32 v20, 5, v162
	v_bfe_u32 v26, v13, 5, 2
	v_lshrrev_b32_e32 v1, 1, v1
	v_add3_u32 v15, 0, v24, v15
	v_lshlrev_b32_e32 v22, 4, v0
	v_and_or_b32 v11, v27, 48, v25
	v_or_b32_e32 v1, v1, v26
	s_waitcnt vmcnt(0)
	v_and_b32_e32 v17, 0x70, v0
	v_lshlrev_b32_e32 v10, 6, v21
	v_and_b32_e32 v18, 48, v14
	v_lshrrev_b32_e32 v11, 1, v11
	v_lshlrev_b32_e32 v1, 9, v1
	v_lshlrev_b32_e32 v23, 1, v0
	v_bitop3_b32 v14, v14, v24, v17 bitop3:0xde
	v_or_b32_e32 v11, v11, v26
	v_or3_b32 v17, v1, v10, v18
	v_and_b32_e32 v1, 0x118, v13
	v_and_b32_e32 v13, 1, v0
	v_and_b32_e32 v28, 0xc0, v22
	v_and_b32_e32 v23, 32, v23
	v_lshlrev_b32_e32 v11, 9, v11
	s_cmp_lg_u32 0, -1
	v_cmp_eq_u32_e64 s[4:5], 0, v13
	v_and_b32_e32 v13, 15, v0
	v_or3_b32 v10, v11, v10, v18
	v_or3_b32 v1, v23, v28, v1
	s_cselect_b32 s0, 0, 0
	v_lshlrev_b32_e32 v170, 4, v13
	v_lshlrev_b32_e32 v13, 7, v0
	s_mov_b32 s13, 0
	v_add_u32_e32 v1, s0, v1
	v_lshlrev_b32_e32 v163, 2, v20
	v_cmp_gt_u32_e64 s[0:1], 32, v162
	v_lshlrev_b32_e32 v168, 13, v20
	s_waitcnt vmcnt(11)
	ds_write_b128 v15, v[2:5] offset:32768
	s_waitcnt vmcnt(10)
	ds_write_b128 v15, v[6:9] offset:40960
	v_lshlrev_b32_e32 v2, 4, v20
	v_and_b32_e32 v4, 0x70, v22
	v_or_b32_e32 v6, 32, v2
	v_xad_u32 v7, v6, v4, 0
	v_or_b32_e32 v6, 64, v2
	v_xad_u32 v5, v2, v4, 0
	v_xad_u32 v9, v6, v4, 0
	v_or_b32_e32 v2, 0x60, v2
	v_lshlrev_b32_e32 v6, 10, v27
	v_lshlrev_b32_e32 v3, 8, v30
	v_xad_u32 v11, v2, v4, 0
	v_or_b32_e32 v2, 0x10000, v16
	v_or_b32_e32 v4, 0x18000, v16
	v_lshlrev_b32_e32 v8, 3, v20
	v_lshlrev_b32_e32 v178, 1, v6
	v_mbcnt_lo_u32_b32 v6, -1, 0
	v_mov_b32_e32 v169, v167
	v_lshl_or_b32 v254, v30, 9, 16
	v_mov_b32_e32 v171, v167
	v_and_b32_e32 v252, 0xf800, v13
	v_mov_b32_e32 v253, v167
	s_mov_b32 s74, 0xff800000
	s_mov_b32 s75, 0x41000000
	s_mov_b32 s14, 0x3e0293ee
	s_mov_b32 s76, 0x40000
	s_mov_b32 s77, 0x50000
	v_lshlrev_b32_e32 v164, 1, v16
	v_lshlrev_b32_e32 v176, 1, v12
	v_lshlrev_b32_e32 v180, 1, v8
	v_mbcnt_hi_u32_b32 v196, -1, v6
	v_lshlrev_b32_e32 v166, 1, v30
	v_add_u32_e32 v197, 0, v17
	v_add_u32_e32 v198, 0, v10
	v_lshlrev_b32_e32 v182, 1, v2
	v_lshlrev_b32_e32 v184, 1, v4
	v_add_u32_e32 v199, v5, v3
	v_add_u32_e32 v200, v7, v3
	v_add_u32_e32 v201, v9, v3
	v_add_u32_e32 v202, v11, v3
	v_mov_b32_e32 v203, 0xf149f2ca
	v_add_u32_e32 v204, 0, v14
	s_mov_b32 s79, 0
	s_mov_b32 s78, s2
	s_waitcnt lgkmcnt(0)
	s_barrier
	s_branch .LBB0_1293

; #define SBAR() __builtin_amdgcn_sched_barrier(0)
; __device__ __forceinline__ int v_st(int k, int c) { const int kk = (k & ~0xC) | ((k & 4) << 1) | ((k & 8) >> 1); return ((kk >> 3) * 4 + (c >> 5)) * 512 + ((kk & 7) * 32 + (c & 31)) * 2; }
; __device__ __forceinline__ int v_rd_base(int lane) { return ((lane & 3) << 3) | (((lane >> 2) & 3) << 6) | (((lane >> 4) & 1) << 5) | (((lane >> 5) & 1) << 8); }
; #define VMW() asm volatile("s_waitcnt vmcnt(0)" ::: "memory")
; #define SLOAD_H(Kp, Vp, k0) do { S.st_v0 = load8(ROW(Vp, k0, sr)); S.st_v1 = load8(ROW(Vp, k0, 32 + sr));              \
;                          S.st_k0 = load8(ROW(Kp, k0, sr)); S.st_k1 = load8(ROW(Kp, k0, 32 + sr)); } while (0)
; #define SWRITE_HV(bf) do { *(bf16x8*)(V_lds + (bf) * SHM_V + vst0) = S.st_v0; *(bf16x8*)(V_lds + (bf) * SHM_V + vst1) = S.st_v1; } while (0)
; #define SWRITE_H(bf) do { SWRITE_HV(bf); SWRITE_HK(bf); } while (0)
; #define MASKT(P0_, P1_) sel_mask_tile(P0_, P1_, mw.x, mw.y, hi)
; __device__ __forceinline__ void attn_block(const BlockRef& cur, const BlockRef& nxt, char* lds, Seam& S) {
;     ...
;     const int sr = tid >> 4, sc = (tid & 15) * 8, vst0 = v_st(sr, sc), vst1 = v_st(32 + sr, sc), kws = KSWZ(sr, sc * 2);
;     const int vb0 = (int)(uintptr_t)V_lds + v_rd_base(lane);
;     const bf16* Kh = cur.K; const bf16* Vh = cur.V;
;     const unsigned mrow_off = (unsigned)(wid * QBLK + r32) * 512u;
;     u32x2 mw;
;     ...
;     SWRITE_HV(0); SBAR();
;     mw = LDMASK(0);
;     if (NT > 1) { SLOAD_H(Kh, Vh, KBASE(1)); }
;     SBAR(); qkt<0>(pA0, pA1, K_lds, r32, hi, S.qr);
;     MASKT(pA0, pA1); partialSM(pA0, pA1, m_reg, mnA, alA);
;     if (NT > 1) { VMW(); SWRITE_H(1); }
;     __syncthreads();
.LBB0_1298:
	v_readfirstlane_b32 s83, v0
	s_lshr_b32 s12, s38, 6
	s_or_b32 s81, s12, 3
	s_and_b32 s12, s83, 0x3fffffc0
	s_lshl_b32 s12, s12, 2
	s_add_i32 s84, s12, 0
	s_lshr_b32 s12, s83, 1
	s_and_b32 s12, s12, 0x7fffffe0
	v_and_b32_e32 v88, 31, v0
	v_or_b32_e32 v186, s12, v88
	s_mov_b32 s82, 1
	v_lshlrev_b32_e32 v165, 9, v186
	s_add_i32 s84, s84, 0x10000
	s_waitcnt vmcnt(1)
	ds_write_b128 v197, v[130:133]
	s_waitcnt vmcnt(0)
	ds_write_b128 v198, v[134:137]
	v_mov_b32_e32 v183, v167
	v_lshl_add_u64 v[2:3], s[70:71], 0, v[182:183]
	v_mov_b32_e32 v177, v167
	v_mov_b32_e32 v185, v167
	v_lshl_add_u64 v[2:3], v[2:3], 0, v[176:177]
	v_lshl_add_u64 v[4:5], s[70:71], 0, v[184:185]
	global_load_dwordx2 v[86:87], v165, s[68:69]
	v_lshl_add_u64 v[4:5], v[4:5], 0, v[176:177]
	global_load_dwordx4 v[50:53], v[2:3], off
	global_load_dwordx4 v[54:57], v[4:5], off
	v_lshl_add_u64 v[2:3], s[6:7], 0, v[182:183]
	v_lshl_add_u64 v[2:3], v[2:3], 0, v[176:177]
	v_lshl_add_u64 v[4:5], s[6:7], 0, v[184:185]
	v_lshl_add_u64 v[4:5], v[4:5], 0, v[176:177]
	global_load_dwordx4 v[58:61], v[2:3], off
	global_load_dwordx4 v[62:65], v[4:5], off
	ds_read_b128 v[2:5], v199 offset:32768
	ds_read_b128 v[6:9], v199 offset:32896
	s_mov_b32 s36, s13
	s_mov_b32 s37, s13
	s_mov_b32 s38, s13
	s_waitcnt lgkmcnt(1)
	v_mfma_f32_32x32x16_bf16 v[34:49], v[2:5], v[126:129], 0
	ds_read_b128 v[2:5], v199 offset:40960
	ds_read_b128 v[10:13], v199 offset:41088
	s_mov_b32 s39, s13
	s_mov_b32 s40, s13
	s_mov_b32 s41, s13
	s_mov_b32 s42, s13
	s_mov_b32 s43, s13
	s_mov_b32 s44, s13
	s_waitcnt lgkmcnt(1)
	v_mfma_f32_32x32x16_bf16 v[18:33], v[2:5], v[126:129], 0
	ds_read_b128 v[2:5], v200 offset:32768
	ds_read_b128 v[14:17], v200 offset:32896
	s_mov_b32 s45, s13
	s_mov_b32 s46, s13
	s_mov_b32 s47, s13
	s_mov_b32 s48, s13
	s_mov_b32 s49, s13
	s_mov_b32 s50, s13
	s_waitcnt lgkmcnt(1)
	v_mfma_f32_32x32x16_bf16 v[34:49], v[2:5], v[122:125], v[34:49]
	ds_read_b128 v[2:5], v200 offset:40960
	ds_read_b128 v[66:69], v200 offset:41088
	s_mov_b32 s51, s13
	v_lshl_add_u32 v185, v88, 2, s84
	v_lshl_add_u32 v183, v163, 2, s84
	v_add_u32_e32 v188, v170, v252
	s_mov_b64 s[16:17], s[70:71]
	s_mov_b64 s[100:101], s[6:7]
	v_mov_b32_e32 v205, 0
	s_waitcnt lgkmcnt(1)
	v_mfma_f32_32x32x16_bf16 v[18:33], v[2:5], v[122:125], v[18:33]
	ds_read_b128 v[2:5], v201 offset:32768
	ds_read_b128 v[70:73], v201 offset:32896
	s_waitcnt lgkmcnt(1)
	v_mfma_f32_32x32x16_bf16 v[34:49], v[2:5], v[118:121], v[34:49]
	ds_read_b128 v[2:5], v201 offset:40960
	ds_read_b128 v[74:77], v201 offset:41088
	s_waitcnt lgkmcnt(1)
	v_mfma_f32_32x32x16_bf16 v[18:33], v[2:5], v[118:121], v[18:33]
	ds_read_b128 v[2:5], v202 offset:32768
	ds_read_b128 v[78:81], v202 offset:32896
	s_waitcnt lgkmcnt(1)
	v_mfma_f32_32x32x16_bf16 v[34:49], v[2:5], v[114:117], v[34:49]
	ds_read_b128 v[2:5], v202 offset:40960
	ds_read_b128 v[82:85], v202 offset:41088
	s_waitcnt vmcnt(0)
	s_waitcnt vmcnt(3)
	ds_write_b128 v197, v[50:53] offset:16384
	s_waitcnt vmcnt(2)
	ds_write_b128 v198, v[54:57] offset:16384
	s_waitcnt vmcnt(1)
	ds_write_b128 v204, v[58:61] offset:49152
	s_waitcnt vmcnt(0)
	ds_write_b128 v204, v[62:65] offset:57344
	s_waitcnt lgkmcnt(0)
	s_barrier
	v_mfma_f32_32x32x16_bf16 v[34:49], v[6:9], v[110:113], v[34:49]
	v_mfma_f32_32x32x16_bf16 v[18:33], v[2:5], v[114:117], v[18:33]
	v_mfma_f32_32x32x16_bf16 v[34:49], v[14:17], v[106:109], v[34:49]
	v_mfma_f32_32x32x16_bf16 v[18:33], v[10:13], v[110:113], v[18:33]
	v_mov_b64_e32 v[2:3], s[36:37]
	v_mov_b64_e32 v[4:5], s[38:39]
	v_mov_b64_e32 v[6:7], s[40:41]
	v_mov_b64_e32 v[8:9], s[42:43]
	v_mov_b64_e32 v[10:11], s[44:45]
	v_mov_b64_e32 v[12:13], s[46:47]
	v_mov_b64_e32 v[14:15], s[48:49]
	v_mfma_f32_32x32x16_bf16 v[34:49], v[70:73], v[102:105], v[34:49]
	v_mov_b64_e32 v[16:17], s[50:51]
	v_mov_b64_e32 v[64:65], v[16:17]
	v_mov_b64_e32 v[62:63], v[14:15]
	v_mov_b64_e32 v[60:61], v[12:13]
	v_mov_b64_e32 v[58:59], v[10:11]
	v_mov_b64_e32 v[56:57], v[8:9]
	v_mov_b64_e32 v[54:55], v[6:7]
	v_mfma_f32_32x32x16_bf16 v[18:33], v[66:69], v[106:109], v[18:33]
	v_lshrrev_b32_e32 v66, v163, v86
	v_bfe_i32 v68, v66, 0, 1
	v_lshrrev_b32_e32 v67, v163, v87
	v_bfe_i32 v69, v67, 0, 1
	v_bfe_i32 v70, v67, 2, 1
	v_bfe_i32 v71, v67, 3, 1
	v_bfe_i32 v72, v67, 8, 1
	v_mfma_f32_32x32x16_bf16 v[34:49], v[78:81], v[98:101], v[34:49]
	v_bfe_i32 v73, v67, 9, 1
	v_bfe_i32 v78, v67, 18, 1
	v_bfe_i32 v79, v67, 19, 1
	v_bfe_i32 v80, v67, 24, 1
	v_bfe_i32 v81, v67, 25, 1
	v_mov_b64_e32 v[52:53], v[4:5]
	v_mov_b64_e32 v[50:51], v[2:3]
	v_mfma_f32_32x32x16_bf16 v[18:33], v[74:77], v[102:105], v[18:33]
	s_nop 3
	v_bitop3_b32 v68, v34, s74, v68 bitop3:0xe4
	v_bfe_i32 v34, v66, 1, 1
	v_bitop3_b32 v35, v35, s74, v34 bitop3:0xe4
	v_bfe_i32 v34, v66, 2, 1
	v_bitop3_b32 v36, v36, s74, v34 bitop3:0xe4
	v_bfe_i32 v34, v66, 3, 1
	v_bitop3_b32 v37, v37, s74, v34 bitop3:0xe4
	v_bfe_i32 v34, v66, 8, 1
	v_bitop3_b32 v38, v38, s74, v34 bitop3:0xe4
	v_bfe_i32 v34, v66, 9, 1
	v_bitop3_b32 v39, v39, s74, v34 bitop3:0xe4
	v_bfe_i32 v34, v66, 10, 1
	v_bitop3_b32 v40, v40, s74, v34 bitop3:0xe4
	v_bfe_i32 v34, v66, 11, 1
	v_mfma_f32_32x32x16_bf16 v[18:33], v[82:85], v[98:101], v[18:33]
	v_bitop3_b32 v41, v41, s74, v34 bitop3:0xe4
	v_bfe_i32 v34, v66, 16, 1
	v_bitop3_b32 v42, v42, s74, v34 bitop3:0xe4
	v_bfe_i32 v34, v66, 17, 1
	v_bitop3_b32 v43, v43, s74, v34 bitop3:0xe4
	v_bfe_i32 v34, v66, 18, 1
	v_bitop3_b32 v44, v44, s74, v34 bitop3:0xe4
	v_bfe_i32 v34, v66, 19, 1
	v_bitop3_b32 v45, v45, s74, v34 bitop3:0xe4
	v_bfe_i32 v34, v66, 24, 1
	v_bitop3_b32 v46, v46, s74, v34 bitop3:0xe4
	v_bfe_i32 v34, v66, 25, 1
	v_bitop3_b32 v47, v47, s74, v34 bitop3:0xe4
; __device__ __forceinline__ void sel_mask_tile(f32x16& p0, f32x16& p1, unsigned wlo, unsigned whi, int hi) {
;     const unsigned NEGB = 0xff800000u;
;     const unsigned lo = wlo >> (4 * hi), h2 = whi >> (4 * hi);
; #pragma unroll
;     for (int r = 0; r < 16; ++r) {
;         const int c = (r & 3) + 8 * (r >> 2);
;         const unsigned m0 = (unsigned)__builtin_amdgcn_sbfe((int)lo, c, 1), m1 = (unsigned)__builtin_amdgcn_sbfe((int)h2, c, 1);
;         p0[r] = __uint_as_float((__float_as_uint(p0[r]) & m0) | (NEGB & ~m0));
;         p1[r] = __uint_as_float((__float_as_uint(p1[r]) & m1) | (NEGB & ~m1));
;     }
; }
; __device__ __forceinline__ void partialSM(f32x16& p0, f32x16& p1, float& m_reg, float& mn, float& alpha) {
;     float pmax = p0[0];
; #pragma unroll
;     for (int r = 1; r < 16; ++r) pmax = fmaxf(pmax, p0[r]);
; #pragma unroll
;     for (int r = 0; r < 16; ++r) pmax = fmaxf(pmax, p1[r]);
;     { auto rr = __builtin_amdgcn_permlane32_swap(__float_as_uint(pmax), __float_as_uint(pmax), false, false);
;       pmax = fmaxf(__uint_as_float(rr[0]), __uint_as_float(rr[1])); }
;     constexpr float C2 = 1.4426950408889634f * SCALE;
;     if (__builtin_expect(__all((pmax - m_reg) * SCALE <= THR), 1)) { mn = m_reg; alpha = 1.f; }
;     else { mn = fmaxf(m_reg, pmax); alpha = __builtin_amdgcn_exp2f((m_reg - mn) * C2); m_reg = mn; }
;     const float mnL = -mn * C2;
; #pragma unroll
;     for (int r = 0; r < 16; ++r) p0[r] = fmaf(p0[r], C2, mnL);
; #pragma unroll
;     for (int r = 0; r < 16; ++r) p1[r] = fmaf(p1[r], C2, mnL);
; #pragma unroll
;     for (int r = 0; r < 16; ++r) p0[r] = __builtin_amdgcn_exp2f(p0[r]);
	v_bfe_i32 v34, v66, 26, 1
	v_bitop3_b32 v48, v48, s74, v34 bitop3:0xe4
	v_bfe_i32 v34, v66, 27, 1
	v_bitop3_b32 v18, v18, s74, v69 bitop3:0xe4
	v_bfe_i32 v69, v67, 1, 1
	v_bfe_i32 v74, v67, 10, 1
	v_bfe_i32 v75, v67, 11, 1
	v_bfe_i32 v76, v67, 16, 1
	v_bfe_i32 v77, v67, 17, 1
	v_bfe_i32 v82, v67, 26, 1
	v_bfe_i32 v66, v67, 27, 1
	v_bitop3_b32 v49, v49, s74, v34 bitop3:0xe4
	v_max_f32_e32 v34, v35, v35
	v_max_f32_e32 v67, v68, v68
	v_max_f32_e32 v34, v67, v34
	v_max3_f32 v34, v34, v36, v37
	v_max3_f32 v34, v34, v38, v39
	v_max3_f32 v34, v34, v40, v41
	v_max3_f32 v34, v34, v42, v43
	v_max3_f32 v34, v34, v44, v45
	v_max3_f32 v34, v34, v46, v47
	v_max3_f32 v34, v34, v48, v49
	v_bitop3_b32 v19, v19, s74, v69 bitop3:0xe4
	v_bitop3_b32 v20, v20, s74, v70 bitop3:0xe4
	v_max3_f32 v34, v34, v18, v19
	v_bitop3_b32 v21, v21, s74, v71 bitop3:0xe4
	v_bitop3_b32 v22, v22, s74, v72 bitop3:0xe4
	v_max3_f32 v34, v34, v20, v21
	v_bitop3_b32 v23, v23, s74, v73 bitop3:0xe4
	v_bitop3_b32 v24, v24, s74, v74 bitop3:0xe4
	v_max3_f32 v34, v34, v22, v23
	v_bitop3_b32 v25, v25, s74, v75 bitop3:0xe4
	v_bitop3_b32 v26, v26, s74, v76 bitop3:0xe4
	v_max3_f32 v34, v34, v24, v25
	v_bitop3_b32 v27, v27, s74, v77 bitop3:0xe4
	v_bitop3_b32 v28, v28, s74, v78 bitop3:0xe4
	v_max3_f32 v34, v34, v26, v27
	v_bitop3_b32 v29, v29, s74, v79 bitop3:0xe4
	v_bitop3_b32 v30, v30, s74, v80 bitop3:0xe4
	v_max3_f32 v34, v34, v28, v29
	v_bitop3_b32 v31, v31, s74, v81 bitop3:0xe4
	v_bitop3_b32 v32, v32, s74, v82 bitop3:0xe4
	v_max3_f32 v34, v34, v30, v31
	v_bitop3_b32 v33, v33, s74, v66 bitop3:0xe4
	v_max3_f32 v34, v34, v32, v33
	v_mov_b32_e32 v66, v34
	s_nop 1
	v_permlane32_swap_b32_e32 v34, v66
	v_max_f32_e32 v66, v66, v66
	v_max_f32_e32 v34, v34, v34
	v_max_f32_e32 v34, v34, v66
	v_add_f32_e32 v66, 0x7149f2ca, v34
	v_mul_f32_e32 v66, 0x3db504f3, v66
	v_max_f32_e32 v34, 0xf149f2ca, v34
	v_cmp_ge_f32_e32 vcc, s75, v66
	v_sub_f32_e32 v66, 0xf149f2ca, v34
	v_mul_f32_e32 v66, 0x3e0293ee, v66
	s_cmp_eq_u64 vcc, exec
	v_exp_f32_e32 v66, v66
	s_cselect_b64 vcc, -1, 0
	v_cndmask_b32_e32 v206, v34, v203, vcc
	v_mul_f32_e32 v34, 0xbe0293ee, v206
	v_mov_b32_e32 v67, v34
	v_cndmask_b32_e64 v177, v66, 1.0, vcc
	v_fmamk_f32 v66, v68, 0x3e0293ee, v34
	v_fmamk_f32 v35, v35, 0x3e0293ee, v34
	v_fmamk_f32 v36, v36, 0x3e0293ee, v34
	v_fmamk_f32 v37, v37, 0x3e0293ee, v34
	v_fmamk_f32 v38, v38, 0x3e0293ee, v34
	v_fmamk_f32 v39, v39, 0x3e0293ee, v34
	v_fmamk_f32 v40, v40, 0x3e0293ee, v34
	v_fmamk_f32 v41, v41, 0x3e0293ee, v34
	v_fmamk_f32 v42, v42, 0x3e0293ee, v34
	v_fmamk_f32 v43, v43, 0x3e0293ee, v34
	v_fmamk_f32 v44, v44, 0x3e0293ee, v34
	v_fmamk_f32 v45, v45, 0x3e0293ee, v34
	v_fmamk_f32 v46, v46, 0x3e0293ee, v34
	v_fmamk_f32 v47, v47, 0x3e0293ee, v34
	v_fmamk_f32 v48, v48, 0x3e0293ee, v34
	v_fmac_f32_e32 v67, 0x3e0293ee, v49
	v_exp_f32_e32 v219, v66
	v_exp_f32_e32 v220, v35
	v_exp_f32_e32 v221, v36
	v_exp_f32_e32 v222, v37
	v_exp_f32_e32 v223, v38
	v_exp_f32_e32 v225, v39
	v_exp_f32_e32 v224, v40
	v_exp_f32_e32 v226, v41
	v_exp_f32_e32 v211, v42
	v_exp_f32_e32 v212, v43
	v_exp_f32_e32 v213, v44
	v_exp_f32_e32 v215, v45
	v_exp_f32_e32 v214, v46
	v_exp_f32_e32 v216, v47
	v_exp_f32_e32 v217, v48
	v_exp_f32_e32 v218, v67
	s_lshl_b32 s36, s83, 8
	v_pk_fma_f32 v[152:153], v[32:33], s[14:15], v[34:35] op_sel_hi:[1,0,0]
	v_pk_fma_f32 v[156:157], v[30:31], s[14:15], v[34:35] op_sel_hi:[1,0,0]
	v_pk_fma_f32 v[160:161], v[28:29], s[14:15], v[34:35] op_sel_hi:[1,0,0]
	v_pk_fma_f32 v[150:151], v[26:27], s[14:15], v[34:35] op_sel_hi:[1,0,0]
	v_pk_fma_f32 v[154:155], v[24:25], s[14:15], v[34:35] op_sel_hi:[1,0,0]
	v_pk_fma_f32 v[158:159], v[22:23], s[14:15], v[34:35] op_sel_hi:[1,0,0]
	v_pk_fma_f32 v[192:193], v[20:21], s[14:15], v[34:35] op_sel_hi:[1,0,0]
	v_pk_fma_f32 v[194:195], v[18:19], s[14:15], v[34:35] op_sel_hi:[1,0,0]
	s_and_b32 s36, s36, 0xffffc000
	v_mov_b64_e32 v[48:49], v[16:17]
	v_mov_b64_e32 v[32:33], v[16:17]
	v_or_b32_e32 v179, s36, v254
	v_mov_b64_e32 v[46:47], v[14:15]
	v_mov_b64_e32 v[44:45], v[12:13]
	v_mov_b64_e32 v[42:43], v[10:11]
	v_mov_b64_e32 v[40:41], v[8:9]
	v_mov_b64_e32 v[38:39], v[6:7]
	v_mov_b64_e32 v[36:37], v[4:5]
	v_mov_b64_e32 v[34:35], v[2:3]
	v_mov_b64_e32 v[30:31], v[14:15]
	v_mov_b64_e32 v[28:29], v[12:13]
	v_mov_b64_e32 v[26:27], v[10:11]
	v_mov_b64_e32 v[24:25], v[8:9]
	v_mov_b64_e32 v[22:23], v[6:7]
	v_mov_b64_e32 v[20:21], v[4:5]
	v_mov_b64_e32 v[18:19], v[2:3]
; template <int KB>
; __device__ __forceinline__ void qkt(f32x16& p0, f32x16& p1, const char* K_lds, int r32, int hi, const bf16x8* qr) {
;     p0 = f32x16{}; p1 = f32x16{};
;     const char* kb[4];
; #pragma unroll
;     for (int dd = 0; dd < 4; ++dd) kb[dd] = K_lds + KB * SHM_K + KSWZ(r32, (dd * 16 + hi * 8) * 2);
; #pragma unroll
;     for (int d0 = 0; d0 < 8; ++d0) { const char* a = kb[d0 & 3] + (d0 >> 2) * 128;
;         bf16x8 b0 = *reinterpret_cast<const bf16x8*>(a);
;         bf16x8 b1 = *reinterpret_cast<const bf16x8*>(a + 32 * 256);
;         p0 = __builtin_amdgcn_mfma_f32_32x32x16_bf16(b0, qr[d0], p0, 0, 0, 0);
;         p1 = __builtin_amdgcn_mfma_f32_32x32x16_bf16(b1, qr[d0], p1, 0, 0, 0); }
; }
.LBB0_1299:
	global_load_dwordx2 v[146:147], v179, s[68:69] offset:-8
	s_add_u32 s98, s16, 0x40000
	s_addc_u32 s99, s17, 0
	global_load_dwordx4 v[130:133], v188, s[98:99]
	s_add_u32 s98, s16, 0x50000
	s_addc_u32 s99, s17, 0
	global_load_dwordx4 v[134:137], v188, s[98:99]
	s_add_u32 s98, s100, 0x40000
	s_addc_u32 s99, s101, 0
	global_load_dwordx4 v[138:141], v188, s[98:99]
	s_add_u32 s98, s100, 0x50000
	s_addc_u32 s99, s101, 0
	global_load_dwordx4 v[142:145], v188, s[98:99]
	ds_read_b128 v[66:69], v199 offset:49152
	ds_read_b128 v[82:85], v199 offset:57344
	ds_read_b128 v[172:175], v200 offset:49152
	ds_read_b128 v[232:235], v200 offset:57344
	ds_read_b128 v[236:239], v201 offset:49152
	ds_read_b128 v[240:243], v201 offset:57344
	ds_read_b128 v[244:247], v202 offset:49152
	v_exp_f32_e32 v209, v150
	v_add_f32_e32 v150, v220, v219
	v_add_f32_e32 v150, v221, v150
	s_waitcnt lgkmcnt(6)
	v_mfma_f32_32x32x16_bf16 v[66:81], v[66:69], v[126:129], 0
	v_add_f32_e32 v150, v222, v150
	v_add_f32_e32 v150, v223, v150
	v_add_f32_e32 v150, v225, v150
	v_add_f32_e32 v150, v224, v150
	v_add_f32_e32 v150, v226, v150
	s_waitcnt lgkmcnt(5)
	v_mfma_f32_32x32x16_bf16 v[82:97], v[82:85], v[126:129], 0
	v_add_f32_e32 v150, v211, v150
	v_add_f32_e32 v150, v212, v150
	v_exp_f32_e32 v194, v194
	s_waitcnt lgkmcnt(4)
	v_mfma_f32_32x32x16_bf16 v[66:81], v[172:175], v[122:125], v[66:81]
	ds_read_b128 v[172:175], v202 offset:57344
	v_exp_f32_e32 v195, v195
	v_exp_f32_e32 v192, v192
	v_exp_f32_e32 v193, v193
	s_waitcnt lgkmcnt(4)
	v_mfma_f32_32x32x16_bf16 v[82:97], v[232:235], v[122:125], v[82:97]
	ds_read_b128 v[232:235], v199 offset:49280
	v_exp_f32_e32 v158, v158
	v_exp_f32_e32 v159, v159
	s_waitcnt lgkmcnt(4)
	v_mfma_f32_32x32x16_bf16 v[66:81], v[236:239], v[118:121], v[66:81]
	ds_read_b128 v[236:239], v199 offset:57472
	v_exp_f32_e32 v207, v154
	v_exp_f32_e32 v208, v155
	v_exp_f32_e32 v210, v151
	s_waitcnt lgkmcnt(4)
	v_mfma_f32_32x32x16_bf16 v[82:97], v[240:243], v[118:121], v[82:97]
	ds_read_b128 v[240:243], v200 offset:49280
	v_exp_f32_e32 v160, v160
	v_exp_f32_e32 v161, v161
	s_waitcnt lgkmcnt(4)
	v_mfma_f32_32x32x16_bf16 v[66:81], v[244:247], v[114:117], v[66:81]
	ds_read_b128 v[244:247], v200 offset:57472
	v_exp_f32_e32 v227, v156
	v_cvt_pk_bf16_f32 v151, v224, v226
	v_cvt_pk_bf16_f32 v154, v214, v216
	v_cvt_pk_bf16_f32 v155, v217, v218
	v_cvt_pk_bf16_f32 v156, v194, v195
	s_waitcnt lgkmcnt(4)
	v_mfma_f32_32x32x16_bf16 v[82:97], v[172:175], v[114:117], v[82:97]
	ds_read_b128 v[172:175], v201 offset:49280
	v_exp_f32_e32 v228, v157
	v_exp_f32_e32 v229, v152
	s_waitcnt lgkmcnt(4)
	v_mfma_f32_32x32x16_bf16 v[66:81], v[232:235], v[110:113], v[66:81]
	ds_read_b128 v[232:235], v201 offset:57472
	v_exp_f32_e32 v230, v153
	v_cvt_pk_bf16_f32 v152, v211, v212
	v_cvt_pk_bf16_f32 v153, v213, v215
	v_cvt_pk_bf16_f32 v157, v192, v193
	v_cvt_pk_bf16_f32 v211, v229, v230
	s_waitcnt lgkmcnt(4)
	v_mfma_f32_32x32x16_bf16 v[82:97], v[236:239], v[110:113], v[82:97]
	ds_read_b128 v[236:239], v202 offset:49280
	v_permlane32_swap_b32_e32 v152, v154
	v_permlane32_swap_b32_e32 v153, v155
	v_add_f32_e32 v249, v213, v150
	v_add_f32_e32 v249, v215, v249
	v_add_f32_e32 v249, v214, v249
	s_waitcnt lgkmcnt(4)
	v_mfma_f32_32x32x16_bf16 v[66:81], v[240:243], v[106:109], v[66:81]
	ds_read_b128 v[240:243], v202 offset:57472
	v_add_f32_e32 v249, v216, v249
	v_add_f32_e32 v249, v217, v249
	v_add_f32_e32 v249, v218, v249
	v_add_f32_e32 v249, v194, v249
	v_add_f32_e32 v248, v195, v249
	s_waitcnt lgkmcnt(4)
	v_mfma_f32_32x32x16_bf16 v[82:97], v[244:247], v[106:109], v[82:97]
	v_add_f32_e32 v248, v192, v248
	v_add_f32_e32 v248, v193, v248
	v_add_f32_e32 v248, v158, v248
	v_add_f32_e32 v248, v159, v248
	v_add_f32_e32 v248, v207, v248
	s_waitcnt lgkmcnt(3)
	v_mfma_f32_32x32x16_bf16 v[66:81], v[172:175], v[102:105], v[66:81]
	v_add_f32_e32 v248, v208, v248
	v_add_f32_e32 v248, v209, v248
	v_add_f32_e32 v248, v210, v248
	v_add_f32_e32 v248, v160, v248
	v_add_f32_e32 v248, v161, v248
	s_waitcnt lgkmcnt(2)
	v_mfma_f32_32x32x16_bf16 v[82:97], v[232:235], v[102:105], v[82:97]
	v_add_f32_e32 v248, v227, v248
	v_add_f32_e32 v248, v228, v248
	v_add_f32_e32 v248, v229, v248
	v_add_f32_e32 v181, v230, v248
	s_waitcnt lgkmcnt(1)
	v_mfma_f32_32x32x16_bf16 v[66:81], v[236:239], v[98:101], v[66:81]
	v_cvt_pk_bf16_f32 v148, v219, v220
	v_cvt_pk_bf16_f32 v149, v221, v222
	v_cvt_pk_bf16_f32 v150, v223, v225
	v_cvt_pk_bf16_f32 v158, v158, v159
	v_cvt_pk_bf16_f32 v159, v207, v208
	s_waitcnt lgkmcnt(0)
	v_mfma_f32_32x32x16_bf16 v[82:97], v[240:243], v[98:101], v[82:97]
	v_cvt_pk_bf16_f32 v208, v209, v210
	v_cvt_pk_bf16_f32 v210, v227, v228
	v_permlane32_swap_b32_e32 v148, v150
	v_permlane32_swap_b32_e32 v149, v151
	v_cvt_pk_bf16_f32 v209, v160, v161
	v_permlane32_swap_b32_e32 v208, v210
	v_permlane32_swap_b32_e32 v156, v158
	v_permlane32_swap_b32_e32 v157, v159
	v_permlane32_swap_b32_e32 v209, v211
	ds_read_b64_tr_b16 v[172:173], v1 offset:0x0
	ds_read_b64_tr_b16 v[174:175], v1 offset:0x800
	ds_read_b64_tr_b16 v[212:213], v1 offset:0x200
	ds_read_b64_tr_b16 v[214:215], v1 offset:0xa00
	ds_read_b64_tr_b16 v[216:217], v1 offset:0x400
	ds_read_b64_tr_b16 v[218:219], v1 offset:0xc00
	ds_read_b64_tr_b16 v[220:221], v1 offset:0x600
	ds_read_b64_tr_b16 v[222:223], v1 offset:0xe00
	ds_read_b64_tr_b16 v[224:225], v1 offset:0x1000
	ds_read_b64_tr_b16 v[226:227], v1 offset:0x1800
	ds_read_b64_tr_b16 v[232:233], v1 offset:0x1200
	ds_read_b64_tr_b16 v[234:235], v1 offset:0x1a00
	ds_read_b64_tr_b16 v[236:237], v1 offset:0x1400
	ds_read_b64_tr_b16 v[238:239], v1 offset:0x1c00
	s_nop 0
	s_waitcnt lgkmcnt(12)
; __device__ __forceinline__ void sel_mask_tile(f32x16& p0, f32x16& p1, unsigned wlo, unsigned whi, int hi) {
;     const unsigned NEGB = 0xff800000u;
;     const unsigned lo = wlo >> (4 * hi), h2 = whi >> (4 * hi);
; #pragma unroll
;     for (int r = 0; r < 16; ++r) {
;         const int c = (r & 3) + 8 * (r >> 2);
;         const unsigned m0 = (unsigned)__builtin_amdgcn_sbfe((int)lo, c, 1), m1 = (unsigned)__builtin_amdgcn_sbfe((int)h2, c, 1);
;         p0[r] = __uint_as_float((__float_as_uint(p0[r]) & m0) | (NEGB & ~m0));
;         p1[r] = __uint_as_float((__float_as_uint(p1[r]) & m1) | (NEGB & ~m1));
;     }
; }
; __device__ __forceinline__ void partialSM(f32x16& p0, f32x16& p1, float& m_reg, float& mn, float& alpha) {
;     float pmax = p0[0];
; #pragma unroll
;     for (int r = 1; r < 16; ++r) pmax = fmaxf(pmax, p0[r]);
; #pragma unroll
;     for (int r = 0; r < 16; ++r) pmax = fmaxf(pmax, p1[r]);
;     { auto rr = __builtin_amdgcn_permlane32_swap(__float_as_uint(pmax), __float_as_uint(pmax), false, false);
;       pmax = fmaxf(__uint_as_float(rr[0]), __uint_as_float(rr[1])); }
; template <int VB>
; __device__ __forceinline__ void pv_tile(f32x16* o, int vb0, bf16x8 pa0, bf16x8 pa1, bf16x8 pa2, bf16x8 pa3) {
;     ...
;     PV_D0(0); PV_D0(1); PV_D0(2); PV_D0(3);
	v_mfma_f32_32x32x16_bf16 v[2:17], v[148:151], v[172:175], v[2:17]
	ds_read_b64_tr_b16 v[240:241], v1 offset:0x1600
	ds_read_b64_tr_b16 v[242:243], v1 offset:0x1e00
	s_waitcnt vmcnt(4)
	v_lshrrev_b32_e32 v160, v163, v146
	v_lshrrev_b32_e32 v161, v163, v147
	v_bfe_i32 v146, v160, 0, 1
	v_bfe_i32 v147, v161, 0, 1
	v_bitop3_b32 v146, v66, s74, v146 bitop3:0xe4
	v_bitop3_b32 v66, v82, s74, v147 bitop3:0xe4
	s_waitcnt lgkmcnt(12)
	v_mfma_f32_32x32x16_bf16 v[50:65], v[148:151], v[212:215], v[50:65]
	ds_read_b64_tr_b16 v[244:245], v1 offset:0x2000
	ds_read_b64_tr_b16 v[246:247], v1 offset:0x2800
	v_bfe_i32 v82, v160, 1, 1
	v_bfe_i32 v147, v161, 1, 1
	v_bitop3_b32 v82, v67, s74, v82 bitop3:0xe4
	v_bitop3_b32 v67, v83, s74, v147 bitop3:0xe4
	v_bfe_i32 v83, v160, 2, 1
	v_bfe_i32 v147, v161, 2, 1
	s_waitcnt lgkmcnt(12)
	v_mfma_f32_32x32x16_bf16 v[34:49], v[148:151], v[216:219], v[34:49]
	ds_read_b64_tr_b16 v[248:249], v1 offset:0x2200
	ds_read_b64_tr_b16 v[250:251], v1 offset:0x2a00
	v_bitop3_b32 v83, v68, s74, v83 bitop3:0xe4
	v_bitop3_b32 v68, v84, s74, v147 bitop3:0xe4
	v_bfe_i32 v84, v160, 3, 1
	s_waitcnt lgkmcnt(12)
	v_mfma_f32_32x32x16_bf16 v[18:33], v[148:151], v[220:223], v[18:33]
	ds_read_b64_tr_b16 v[220:221], v1 offset:0x2400
	ds_read_b64_tr_b16 v[222:223], v1 offset:0x2c00
	v_bfe_i32 v148, v161, 3, 1
	v_bitop3_b32 v147, v69, s74, v84 bitop3:0xe4
	v_bfe_i32 v84, v160, 8, 1
	v_bitop3_b32 v69, v85, s74, v148 bitop3:0xe4
	v_bfe_i32 v85, v161, 8, 1
	v_bitop3_b32 v148, v70, s74, v84 bitop3:0xe4
	v_bfe_i32 v84, v160, 9, 1
	s_waitcnt lgkmcnt(12)
	v_mfma_f32_32x32x16_bf16 v[2:17], v[152:155], v[224:227], v[2:17]
	ds_read_b64_tr_b16 v[224:225], v1 offset:0x2600
	ds_read_b64_tr_b16 v[226:227], v1 offset:0x2e00
	v_bitop3_b32 v70, v86, s74, v85 bitop3:0xe4
	v_bfe_i32 v85, v161, 9, 1
	v_bitop3_b32 v149, v71, s74, v84 bitop3:0xe4
	v_bfe_i32 v84, v160, 10, 1
	v_bitop3_b32 v71, v87, s74, v85 bitop3:0xe4
	v_bfe_i32 v85, v161, 10, 1
	s_waitcnt lgkmcnt(12)
	v_mfma_f32_32x32x16_bf16 v[50:65], v[152:155], v[232:235], v[50:65]
	ds_read_b64_tr_b16 v[232:233], v1 offset:0x3000
	ds_read_b64_tr_b16 v[234:235], v1 offset:0x3800
	v_bitop3_b32 v87, v72, s74, v84 bitop3:0xe4
	v_bfe_i32 v84, v160, 11, 1
	v_bitop3_b32 v72, v88, s74, v85 bitop3:0xe4
	v_bfe_i32 v85, v161, 11, 1
	v_bitop3_b32 v88, v73, s74, v84 bitop3:0xe4
	v_bfe_i32 v73, v160, 16, 1
	v_bitop3_b32 v84, v89, s74, v85 bitop3:0xe4
	s_waitcnt lgkmcnt(12)
	v_mfma_f32_32x32x16_bf16 v[34:49], v[152:155], v[236:239], v[34:49]
	ds_read_b64_tr_b16 v[236:237], v1 offset:0x3200
	ds_read_b64_tr_b16 v[238:239], v1 offset:0x3a00
	v_bfe_i32 v85, v161, 16, 1
	v_bitop3_b32 v89, v74, s74, v73 bitop3:0xe4
	v_bfe_i32 v73, v160, 17, 1
	v_bfe_i32 v74, v161, 17, 1
	v_bitop3_b32 v85, v90, s74, v85 bitop3:0xe4
	v_bitop3_b32 v90, v75, s74, v73 bitop3:0xe4
	s_waitcnt lgkmcnt(12)
	v_mfma_f32_32x32x16_bf16 v[18:33], v[152:155], v[240:243], v[18:33]
	ds_read_b64_tr_b16 v[240:241], v1 offset:0x3400
	ds_read_b64_tr_b16 v[242:243], v1 offset:0x3c00
	v_bitop3_b32 v86, v91, s74, v74 bitop3:0xe4
	v_bfe_i32 v73, v160, 18, 1
	v_bfe_i32 v74, v161, 18, 1
	v_bitop3_b32 v91, v76, s74, v73 bitop3:0xe4
	v_bitop3_b32 v76, v92, s74, v74 bitop3:0xe4
	v_bfe_i32 v73, v160, 19, 1
	v_bfe_i32 v74, v161, 19, 1
	s_waitcnt lgkmcnt(12)
	v_mfma_f32_32x32x16_bf16 v[2:17], v[156:159], v[244:247], v[2:17]
	ds_read_b64_tr_b16 v[244:245], v1 offset:0x3600
	ds_read_b64_tr_b16 v[246:247], v1 offset:0x3e00
	v_bitop3_b32 v92, v77, s74, v73 bitop3:0xe4
	v_bitop3_b32 v77, v93, s74, v74 bitop3:0xe4
	v_bfe_i32 v73, v160, 24, 1
	v_bfe_i32 v74, v161, 24, 1
	v_bitop3_b32 v93, v78, s74, v73 bitop3:0xe4
	v_bitop3_b32 v78, v94, s74, v74 bitop3:0xe4
	s_waitcnt lgkmcnt(12)
	v_mfma_f32_32x32x16_bf16 v[50:65], v[156:159], v[248:251], v[50:65]
	v_bfe_i32 v73, v160, 25, 1
	v_bfe_i32 v74, v161, 25, 1
	v_bitop3_b32 v79, v79, s74, v73 bitop3:0xe4
	v_bitop3_b32 v73, v95, s74, v74 bitop3:0xe4
	v_bfe_i32 v74, v160, 26, 1
	v_bfe_i32 v75, v161, 26, 1
	v_bitop3_b32 v80, v80, s74, v74 bitop3:0xe4
	s_waitcnt lgkmcnt(10)
	v_mfma_f32_32x32x16_bf16 v[34:49], v[156:159], v[220:223], v[34:49]
	v_bitop3_b32 v74, v96, s74, v75 bitop3:0xe4
	v_bfe_i32 v75, v160, 27, 1
	v_bfe_i32 v94, v161, 27, 1
	v_bitop3_b32 v81, v81, s74, v75 bitop3:0xe4
	v_bitop3_b32 v75, v97, s74, v94 bitop3:0xe4
	s_waitcnt lgkmcnt(8)
	v_mfma_f32_32x32x16_bf16 v[18:33], v[156:159], v[224:227], v[18:33]
	v_max_f32_e32 v94, v146, v82
	v_max3_f32 v94, v94, v83, v147
	v_max3_f32 v94, v94, v148, v149
	v_max3_f32 v94, v94, v87, v88
	v_max3_f32 v94, v94, v89, v90
	v_max3_f32 v94, v94, v91, v92
	s_waitcnt lgkmcnt(6)
	v_mfma_f32_32x32x16_bf16 v[2:17], v[208:211], v[232:235], v[2:17]
	v_max3_f32 v94, v94, v93, v79
	v_max3_f32 v94, v94, v80, v81
	v_max3_f32 v94, v94, v66, v67
	v_max3_f32 v94, v94, v68, v69
	v_max3_f32 v94, v94, v70, v71
	v_max3_f32 v94, v94, v72, v84
	s_waitcnt lgkmcnt(4)
	v_mfma_f32_32x32x16_bf16 v[50:65], v[208:211], v[236:239], v[50:65]
	v_max3_f32 v94, v94, v85, v86
	v_max3_f32 v94, v94, v76, v77
	v_max3_f32 v94, v94, v78, v73
	v_max3_f32 v94, v94, v74, v75
	v_mov_b32_e32 v95, v94
	s_nop 1
	v_permlane32_swap_b32_e32 v94, v95
	s_waitcnt lgkmcnt(2)
	v_mfma_f32_32x32x16_bf16 v[34:49], v[208:211], v[240:243], v[34:49]
	v_max_f32_e32 v94, v94, v95
	v_sub_f32_e32 v95, v94, v206
	v_max_f32_e32 v94, v206, v94
	v_sub_f32_e32 v96, v206, v94
	s_waitcnt lgkmcnt(0)
	v_mfma_f32_32x32x16_bf16 v[18:33], v[208:211], v[244:247], v[18:33]
	s_waitcnt vmcnt(0)
	ds_write_b128 v204, v[138:141] offset:32768
	ds_write_b128 v204, v[142:145] offset:40960
	v_mul_f32_e32 v96, 0x3e0293ee, v96
	v_mul_f32_e32 v95, 0x3db504f3, v95
	v_exp_f32_e32 v96, v96
	v_cmp_ge_f32_e32 vcc, s75, v95
	s_cmp_eq_u64 vcc, exec
	s_cselect_b64 s[6:7], -1, 0
	s_barrier
; __device__ __forceinline__ void partialSM(f32x16& p0, f32x16& p1, float& m_reg, float& mn, float& alpha) {
;     ...
;     const float mnL = -mn * C2;
; #pragma unroll
;     for (int r = 0; r < 16; ++r) p0[r] = fmaf(p0[r], C2, mnL);
; #pragma unroll
;     for (int r = 0; r < 16; ++r) p1[r] = fmaf(p1[r], C2, mnL);
; #pragma unroll
;     for (int r = 0; r < 16; ++r) p0[r] = __builtin_amdgcn_exp2f(p0[r]);
	s_waitcnt vmcnt(0)
	v_cndmask_b32_e64 v208, v96, 1.0, s[6:7]
	v_cmp_gt_f32_e32 vcc, 1.0, v208
	ds_write_b128 v197, v[130:133]
	ds_write_b128 v198, v[134:137]
	s_cbranch_vccz .LBB0_1303
	s_and_saveexec_b64 s[36:37], s[0:1]
	ds_write_b32 v185, v208 offset:128
	s_or_b64 exec, exec, s[36:37]
	s_waitcnt lgkmcnt(0)
	ds_read_b128 v[150:153], v183 offset:224
	ds_read_b128 v[154:157], v183 offset:192
	ds_read_b128 v[158:161], v183 offset:160
	ds_read_b128 v[172:175], v183 offset:128
	s_waitcnt lgkmcnt(3)
	v_pk_mul_f32 v[16:17], v[16:17], v[152:153]
	s_waitcnt lgkmcnt(2)
	v_pk_mul_f32 v[12:13], v[12:13], v[156:157]
	s_waitcnt lgkmcnt(1)
	v_pk_mul_f32 v[8:9], v[8:9], v[160:161]
	s_waitcnt lgkmcnt(0)
	v_pk_mul_f32 v[4:5], v[4:5], v[174:175]
	v_pk_mul_f32 v[14:15], v[14:15], v[150:151]
	v_pk_mul_f32 v[10:11], v[10:11], v[154:155]
	v_pk_mul_f32 v[6:7], v[6:7], v[158:159]
	v_pk_mul_f32 v[2:3], v[2:3], v[172:173]
	v_pk_mul_f32 v[64:65], v[64:65], v[152:153]
	v_pk_mul_f32 v[60:61], v[60:61], v[156:157]
	v_pk_mul_f32 v[56:57], v[56:57], v[160:161]
	v_pk_mul_f32 v[52:53], v[52:53], v[174:175]
	v_pk_mul_f32 v[62:63], v[62:63], v[150:151]
	v_pk_mul_f32 v[58:59], v[58:59], v[154:155]
	v_pk_mul_f32 v[54:55], v[54:55], v[158:159]
	v_pk_mul_f32 v[50:51], v[50:51], v[172:173]
	v_pk_mul_f32 v[48:49], v[48:49], v[152:153]
	v_pk_mul_f32 v[44:45], v[44:45], v[156:157]
	v_pk_mul_f32 v[40:41], v[40:41], v[160:161]
	v_pk_mul_f32 v[36:37], v[36:37], v[174:175]
	v_pk_mul_f32 v[46:47], v[46:47], v[150:151]
	v_pk_mul_f32 v[42:43], v[42:43], v[154:155]
	v_pk_mul_f32 v[38:39], v[38:39], v[158:159]
	v_pk_mul_f32 v[34:35], v[34:35], v[172:173]
	v_pk_mul_f32 v[32:33], v[32:33], v[152:153]
	v_pk_mul_f32 v[28:29], v[28:29], v[156:157]
	v_pk_mul_f32 v[24:25], v[24:25], v[160:161]
	v_pk_mul_f32 v[20:21], v[20:21], v[174:175]
	v_pk_mul_f32 v[30:31], v[30:31], v[150:151]
	v_pk_mul_f32 v[26:27], v[26:27], v[154:155]
	v_pk_mul_f32 v[22:23], v[22:23], v[158:159]
	v_pk_mul_f32 v[18:19], v[18:19], v[172:173]
.LBB0_1303:
	v_cndmask_b32_e64 v206, v94, v206, s[6:7]
	v_mul_f32_e32 v207, 0xbe0293ee, v206
	v_fmamk_f32 v94, v146, 0x3e0293ee, v207
	v_fmamk_f32 v82, v82, 0x3e0293ee, v207
	v_fmamk_f32 v83, v83, 0x3e0293ee, v207
	v_fmamk_f32 v95, v147, 0x3e0293ee, v207
	v_fmamk_f32 v96, v148, 0x3e0293ee, v207
	v_fmamk_f32 v97, v149, 0x3e0293ee, v207
	v_fmamk_f32 v87, v87, 0x3e0293ee, v207
	v_fmamk_f32 v88, v88, 0x3e0293ee, v207
	v_fmamk_f32 v89, v89, 0x3e0293ee, v207
	v_fmamk_f32 v90, v90, 0x3e0293ee, v207
	v_fmamk_f32 v91, v91, 0x3e0293ee, v207
	v_fmamk_f32 v92, v92, 0x3e0293ee, v207
	v_fmamk_f32 v93, v93, 0x3e0293ee, v207
	v_fmamk_f32 v79, v79, 0x3e0293ee, v207
	v_fmamk_f32 v80, v80, 0x3e0293ee, v207
	v_fmamk_f32 v81, v81, 0x3e0293ee, v207
	v_exp_f32_e32 v146, v94
	v_exp_f32_e32 v147, v82
	v_exp_f32_e32 v148, v83
	v_exp_f32_e32 v159, v95
	v_exp_f32_e32 v160, v96
	v_exp_f32_e32 v161, v97
	v_exp_f32_e32 v149, v87
	v_exp_f32_e32 v158, v88
	v_exp_f32_e32 v150, v89
	v_exp_f32_e32 v151, v90
	v_exp_f32_e32 v155, v91
	v_exp_f32_e32 v157, v92
	v_exp_f32_e32 v152, v93
	v_exp_f32_e32 v153, v79
	v_exp_f32_e32 v154, v80
	v_exp_f32_e32 v156, v81
	v_fmamk_f32 v210, v71, 0x3e0293ee, v207
	v_fmamk_f32 v209, v78, 0x3e0293ee, v207
	v_fmamk_f32 v217, v66, 0x3e0293ee, v207
	v_fmamk_f32 v218, v67, 0x3e0293ee, v207
	v_fmamk_f32 v219, v68, 0x3e0293ee, v207
	v_fmamk_f32 v220, v69, 0x3e0293ee, v207
	v_fmamk_f32 v221, v70, 0x3e0293ee, v207
	v_fmamk_f32 v211, v72, 0x3e0293ee, v207
	v_fmamk_f32 v212, v84, 0x3e0293ee, v207
	v_fmamk_f32 v213, v85, 0x3e0293ee, v207
	v_fmamk_f32 v214, v86, 0x3e0293ee, v207
	v_fmamk_f32 v215, v76, 0x3e0293ee, v207
	v_fmamk_f32 v216, v77, 0x3e0293ee, v207
	v_fmamk_f32 v222, v73, 0x3e0293ee, v207
	v_fmamk_f32 v223, v74, 0x3e0293ee, v207
	v_fmac_f32_e32 v207, 0x3e0293ee, v75
	s_waitcnt lgkmcnt(0)
	s_barrier
	global_load_dwordx2 v[228:229], v179, s[68:69]
	s_add_i32 s98, s82, 2
	s_cmp_gt_u32 s98, s81
	s_cbranch_scc1 .Lp5_a2
	s_add_u32 s98, s16, 0x60000
	s_addc_u32 s99, s17, 0
	global_load_dwordx4 v[130:133], v188, s[98:99]
	s_add_u32 s98, s16, 0x70000
	s_addc_u32 s99, s17, 0
	global_load_dwordx4 v[134:137], v188, s[98:99]
	s_add_u32 s98, s100, 0x60000
	s_addc_u32 s99, s101, 0
	global_load_dwordx4 v[138:141], v188, s[98:99]
	s_add_u32 s98, s100, 0x70000
	s_addc_u32 s99, s101, 0
	global_load_dwordx4 v[142:145], v188, s[98:99]

; __device__ __forceinline__ void partialSM(f32x16& p0, f32x16& p1, float& m_reg, float& mn, float& alpha) {
;     ...
;     else { mn = fmaxf(m_reg, pmax); alpha = __builtin_amdgcn_exp2f((m_reg - mn) * C2); m_reg = mn; }
;     const float mnL = -mn * C2;
; #pragma unroll
;     for (int r = 0; r < 16; ++r) p0[r] = fmaf(p0[r], C2, mnL);
; #pragma unroll
;     for (int r = 0; r < 16; ++r) p1[r] = fmaf(p1[r], C2, mnL);
; #pragma unroll
;     for (int r = 0; r < 16; ++r) p0[r] = __builtin_amdgcn_exp2f(p0[r]);
; __device__ __forceinline__ void attn_block(const BlockRef& cur, const BlockRef& nxt, char* lds, Seam& S) {
;     ...
;     for (int t = 1; t + 1 < NT; t += 2) {
;         HALF_STEP(pB0, pB1, mnB, alB, pA0, pA1, alA, t, 1, 0, 0);
;         HALF_STEP(pA0, pA1, mnA, alA, pB0, pB1, alB, t + 1, 0, 1, 1);
;     }
.LBB0_1311:
	v_cndmask_b32_e64 v206, v76, v206, s[6:7]
	v_mul_f32_e32 v76, 0xbe0293ee, v206
	v_mov_b32_e32 v131, v76
	v_fmamk_f32 v77, v192, 0x3e0293ee, v76
	v_fmamk_f32 v78, v146, 0x3e0293ee, v76
	v_fmamk_f32 v79, v147, 0x3e0293ee, v76
	v_fmamk_f32 v80, v148, 0x3e0293ee, v76
	v_fmamk_f32 v81, v149, 0x3e0293ee, v76
	v_fmamk_f32 v130, v150, 0x3e0293ee, v76
	v_fmamk_f32 v88, v88, 0x3e0293ee, v76
	v_fmamk_f32 v89, v89, 0x3e0293ee, v76
	v_fmamk_f32 v90, v90, 0x3e0293ee, v76
	v_fmamk_f32 v91, v91, 0x3e0293ee, v76
	v_fmamk_f32 v92, v92, 0x3e0293ee, v76
	v_fmamk_f32 v93, v93, 0x3e0293ee, v76
	v_fmamk_f32 v94, v94, 0x3e0293ee, v76
	v_fmamk_f32 v95, v95, 0x3e0293ee, v76
	v_fmamk_f32 v96, v96, 0x3e0293ee, v76
	v_fmac_f32_e32 v131, 0x3e0293ee, v97
	v_exp_f32_e32 v219, v77
	v_exp_f32_e32 v220, v78
	v_exp_f32_e32 v221, v79
	v_exp_f32_e32 v222, v80
	v_exp_f32_e32 v223, v81
	v_exp_f32_e32 v225, v130
	v_exp_f32_e32 v224, v88
	v_exp_f32_e32 v226, v89
	v_exp_f32_e32 v211, v90
	v_exp_f32_e32 v212, v91
	v_exp_f32_e32 v213, v92
	v_exp_f32_e32 v215, v93
	v_exp_f32_e32 v214, v94
	v_exp_f32_e32 v216, v95
	v_exp_f32_e32 v217, v96
	v_exp_f32_e32 v218, v131
	v_pk_fma_f32 v[194:195], v[66:67], s[14:15], v[76:77] op_sel_hi:[1,0,0]
	v_fmac_f32_e32 v181, v177, v205
	v_pk_fma_f32 v[192:193], v[82:83], s[14:15], v[76:77] op_sel_hi:[1,0,0]
	v_pk_fma_f32 v[158:159], v[84:85], s[14:15], v[76:77] op_sel_hi:[1,0,0]
	v_pk_fma_f32 v[154:155], v[86:87], s[14:15], v[76:77] op_sel_hi:[1,0,0]
	v_pk_fma_f32 v[150:151], v[74:75], s[14:15], v[76:77] op_sel_hi:[1,0,0]
	v_pk_fma_f32 v[160:161], v[68:69], s[14:15], v[76:77] op_sel_hi:[1,0,0]
	v_pk_fma_f32 v[156:157], v[70:71], s[14:15], v[76:77] op_sel_hi:[1,0,0]
	v_pk_fma_f32 v[152:153], v[72:73], s[14:15], v[76:77] op_sel_hi:[1,0,0]
	v_fma_f32 v205, v181, v208, v209
	v_add_u32_e32 v179, 16, v179
	s_add_u32 s16, s16, 0x40000
	s_addc_u32 s17, s17, 0
	s_add_u32 s100, s100, 0x40000
	s_addc_u32 s101, s101, 0
	s_cmp_ge_u32 s82, s81
	s_waitcnt lgkmcnt(0)
	s_barrier
	s_cbranch_scc1 .LBB0_1313
	v_mov_b32_e32 v177, v207
	s_branch .LBB0_1299
